# P4/P5 K loops: second-buffer A-fragment LDS address no longer rebuilt by a VALU add each iteration (first-buffer address register + 32768 in the ds_read offset)
# speedup vs baseline: 1.0045x; 1.0045x over previous
.LBB0_1167:
	ds_read_b128 v[148:151], v143
	ds_read_b128 v[152:155], v143 offset:1024
	ds_read_b128 v[156:159], v143 offset:2048
	ds_read_b128 v[160:163], v143 offset:3072
	s_add_u32 s24, s22, 0xfff80080
	s_addc_u32 s25, s23, -1
	s_cmp_eq_u32 s53, 28
	s_cselect_b32 s27, s15, s25
	s_cselect_b32 s26, s49, s24
	s_cselect_b32 s25, s13, s52
	s_cselect_b32 s24, s50, s51

	s_add_i32 m0, s21, 0xc000
	ds_read_b128 v[164:167], v145
	ds_read_b128 v[176:179], v145 offset:1024
	ds_read_b128 v[180:183], v145 offset:2048
	ds_read_b128 v[184:187], v145 offset:3072
	ds_read_b128 v[188:191], v145 offset:4096
	ds_read_b128 v[192:195], v145 offset:5120
	ds_read_b128 v[196:199], v145 offset:6144
	ds_read_b128 v[200:203], v145 offset:7168
	global_load_lds_dwordx4 v128, s[22:23]
	s_add_i32 m0, s21, 0xe000
	s_nop 0

	global_load_lds_dwordx4 v130, s[22:23]
	s_waitcnt lgkmcnt(8)
	s_barrier
	s_waitcnt lgkmcnt(0)


	v_mfma_f32_16x16x32_bf16 v[124:127], v[148:151], v[164:167], v[124:127]
	v_mfma_f32_16x16x32_bf16 v[120:123], v[156:159], v[164:167], v[120:123]
	v_mfma_f32_16x16x32_bf16 v[116:119], v[148:151], v[180:183], v[116:119]
	v_mfma_f32_16x16x32_bf16 v[104:107], v[156:159], v[180:183], v[104:107]
	v_mfma_f32_16x16x32_bf16 v[96:99], v[148:151], v[188:191], v[96:99]
	v_mfma_f32_16x16x32_bf16 v[88:91], v[156:159], v[188:191], v[88:91]
	v_mfma_f32_16x16x32_bf16 v[80:83], v[148:151], v[196:199], v[80:83]
	v_mfma_f32_16x16x32_bf16 v[72:75], v[156:159], v[196:199], v[72:75]
	v_mfma_f32_16x16x32_bf16 v[124:127], v[152:155], v[176:179], v[124:127]
	v_mfma_f32_16x16x32_bf16 v[120:123], v[160:163], v[176:179], v[120:123]
	v_mfma_f32_16x16x32_bf16 v[116:119], v[152:155], v[184:187], v[116:119]
	v_mfma_f32_16x16x32_bf16 v[104:107], v[160:163], v[184:187], v[104:107]
	v_mfma_f32_16x16x32_bf16 v[96:99], v[152:155], v[192:195], v[96:99]
	v_mfma_f32_16x16x32_bf16 v[88:91], v[160:163], v[192:195], v[88:91]
	v_mfma_f32_16x16x32_bf16 v[80:83], v[152:155], v[200:203], v[80:83]
	v_mfma_f32_16x16x32_bf16 v[72:75], v[160:163], v[200:203], v[72:75]

	s_barrier
	s_add_i32 s54, s45, s31
	s_add_u32 s66, s24, s10
	s_addc_u32 s67, s25, s11
	s_mov_b32 m0, s54
	ds_read_b128 v[204:207], v147
	ds_read_b128 v[218:221], v147 offset:1024
	ds_read_b128 v[222:225], v147 offset:2048
	ds_read_b128 v[226:229], v147 offset:3072
	global_load_lds_dwordx4 v172, s[24:25]
	s_add_i32 m0, s54, 0x2000
	s_nop 0

	global_load_lds_dwordx4 v174, s[24:25]
	s_barrier
	s_waitcnt lgkmcnt(0)


	v_mfma_f32_16x16x32_bf16 v[112:115], v[204:207], v[164:167], v[112:115]
	v_mfma_f32_16x16x32_bf16 v[108:111], v[222:225], v[164:167], v[108:111]
	v_mfma_f32_16x16x32_bf16 v[100:103], v[204:207], v[180:183], v[100:103]
	v_mfma_f32_16x16x32_bf16 v[92:95], v[222:225], v[180:183], v[92:95]
	v_mfma_f32_16x16x32_bf16 v[84:87], v[204:207], v[188:191], v[84:87]
	v_mfma_f32_16x16x32_bf16 v[76:79], v[222:225], v[188:191], v[76:79]
	v_mfma_f32_16x16x32_bf16 v[68:71], v[204:207], v[196:199], v[68:71]
	v_mfma_f32_16x16x32_bf16 v[64:67], v[222:225], v[196:199], v[64:67]
	v_mfma_f32_16x16x32_bf16 v[112:115], v[218:221], v[176:179], v[112:115]
	v_mfma_f32_16x16x32_bf16 v[108:111], v[226:229], v[176:179], v[108:111]
	v_mfma_f32_16x16x32_bf16 v[100:103], v[218:221], v[184:187], v[100:103]
	v_mfma_f32_16x16x32_bf16 v[92:95], v[226:229], v[184:187], v[92:95]
	v_mfma_f32_16x16x32_bf16 v[84:87], v[218:221], v[192:195], v[84:87]
	v_mfma_f32_16x16x32_bf16 v[76:79], v[226:229], v[192:195], v[76:79]
	v_mfma_f32_16x16x32_bf16 v[68:71], v[218:221], v[200:203], v[68:71]
	v_mfma_f32_16x16x32_bf16 v[64:67], v[226:229], v[200:203], v[64:67]

	s_mov_b32 m0, s21
	s_add_u32 s68, s26, s10
	s_addc_u32 s69, s27, s11
	s_barrier
	ds_read_b128 v[164:167], v145 offset:16384
	ds_read_b128 v[176:179], v145 offset:17408
	ds_read_b128 v[180:183], v145 offset:18432
	ds_read_b128 v[184:187], v145 offset:19456
	ds_read_b128 v[188:191], v145 offset:20480
	ds_read_b128 v[192:195], v145 offset:21504
	ds_read_b128 v[196:199], v145 offset:22528
	ds_read_b128 v[200:203], v145 offset:23552
	global_load_lds_dwordx4 v172, s[26:27]
	s_mov_b32 m0, s35
	s_nop 0

	global_load_lds_dwordx4 v174, s[26:27]
	s_barrier
	s_waitcnt lgkmcnt(0)


	v_mfma_f32_16x16x32_bf16 v[60:63], v[148:151], v[164:167], v[60:63]
	v_mfma_f32_16x16x32_bf16 v[56:59], v[156:159], v[164:167], v[56:59]
	v_mfma_f32_16x16x32_bf16 v[48:51], v[148:151], v[180:183], v[48:51]
	v_mfma_f32_16x16x32_bf16 v[40:43], v[156:159], v[180:183], v[40:43]
	v_mfma_f32_16x16x32_bf16 v[32:35], v[148:151], v[188:191], v[32:35]
	v_mfma_f32_16x16x32_bf16 v[24:27], v[156:159], v[188:191], v[24:27]
	v_mfma_f32_16x16x32_bf16 v[16:19], v[148:151], v[196:199], v[16:19]
	v_mfma_f32_16x16x32_bf16 v[8:11], v[156:159], v[196:199], v[8:11]
	v_mfma_f32_16x16x32_bf16 v[60:63], v[152:155], v[176:179], v[60:63]
	v_mfma_f32_16x16x32_bf16 v[56:59], v[160:163], v[176:179], v[56:59]
	v_mfma_f32_16x16x32_bf16 v[48:51], v[152:155], v[184:187], v[48:51]
	v_mfma_f32_16x16x32_bf16 v[40:43], v[160:163], v[184:187], v[40:43]
	v_mfma_f32_16x16x32_bf16 v[32:35], v[152:155], v[192:195], v[32:35]
	v_mfma_f32_16x16x32_bf16 v[24:27], v[160:163], v[192:195], v[24:27]
	v_mfma_f32_16x16x32_bf16 v[16:19], v[152:155], v[200:203], v[16:19]
	v_mfma_f32_16x16x32_bf16 v[8:11], v[160:163], v[200:203], v[8:11]

	s_barrier
	s_add_u32 s54, s24, 0x80000
	s_addc_u32 s55, s25, 0
	s_add_i32 s56, s46, s31
	s_mov_b32 m0, s56
	s_nop 0

	global_load_lds_dwordx4 v172, s[54:55]
	s_add_i32 m0, s56, 0x2000
	s_nop 0

	global_load_lds_dwordx4 v174, s[54:55]
	s_waitcnt vmcnt(6)
	s_barrier

	v_mfma_f32_16x16x32_bf16 v[52:55], v[204:207], v[164:167], v[52:55]
	v_mfma_f32_16x16x32_bf16 v[44:47], v[222:225], v[164:167], v[44:47]
	v_mfma_f32_16x16x32_bf16 v[36:39], v[204:207], v[180:183], v[36:39]
	v_mfma_f32_16x16x32_bf16 v[28:31], v[222:225], v[180:183], v[28:31]
	v_mfma_f32_16x16x32_bf16 v[20:23], v[204:207], v[188:191], v[20:23]
	v_mfma_f32_16x16x32_bf16 v[12:15], v[222:225], v[188:191], v[12:15]
	v_mfma_f32_16x16x32_bf16 v[4:7], v[204:207], v[196:199], v[4:7]
	v_mfma_f32_16x16x32_bf16 v[0:3], v[222:225], v[196:199], v[0:3]
	v_mfma_f32_16x16x32_bf16 v[52:55], v[218:221], v[176:179], v[52:55]
	v_mfma_f32_16x16x32_bf16 v[44:47], v[226:229], v[176:179], v[44:47]
	v_mfma_f32_16x16x32_bf16 v[36:39], v[218:221], v[184:187], v[36:39]
	v_mfma_f32_16x16x32_bf16 v[28:31], v[226:229], v[184:187], v[28:31]
	v_mfma_f32_16x16x32_bf16 v[20:23], v[218:221], v[192:195], v[20:23]
	v_mfma_f32_16x16x32_bf16 v[12:15], v[226:229], v[192:195], v[12:15]
	v_mfma_f32_16x16x32_bf16 v[4:7], v[218:221], v[200:203], v[4:7]
	v_mfma_f32_16x16x32_bf16 v[0:3], v[226:229], v[200:203], v[0:3]

	s_add_i32 s54, 0, 0x18000

	s_barrier
	ds_read_b128 v[148:151], v143 offset:32768
	ds_read_b128 v[152:155], v143 offset:33792
	ds_read_b128 v[156:159], v143 offset:34816
	ds_read_b128 v[160:163], v143 offset:35840
	s_add_u32 s26, s26, 0x80000
	s_addc_u32 s27, s27, 0
	s_mov_b32 m0, s36

	ds_read_b128 v[164:167], v145 offset:32768
	ds_read_b128 v[176:179], v145 offset:33792
	ds_read_b128 v[180:183], v145 offset:34816
	ds_read_b128 v[184:187], v145 offset:35840
	ds_read_b128 v[188:191], v145 offset:36864
	ds_read_b128 v[192:195], v145 offset:37888
	ds_read_b128 v[196:199], v145 offset:38912
	ds_read_b128 v[200:203], v145 offset:39936
	global_load_lds_dwordx4 v172, s[26:27]
	s_mov_b32 m0, s37
	s_nop 0

	global_load_lds_dwordx4 v174, s[26:27]
	s_waitcnt lgkmcnt(8)
	s_barrier
	s_waitcnt lgkmcnt(0)


	v_mfma_f32_16x16x32_bf16 v[124:127], v[148:151], v[164:167], v[124:127]
	v_mfma_f32_16x16x32_bf16 v[120:123], v[156:159], v[164:167], v[120:123]
	v_mfma_f32_16x16x32_bf16 v[116:119], v[148:151], v[180:183], v[116:119]
	v_mfma_f32_16x16x32_bf16 v[104:107], v[156:159], v[180:183], v[104:107]
	v_mfma_f32_16x16x32_bf16 v[96:99], v[148:151], v[188:191], v[96:99]
	v_mfma_f32_16x16x32_bf16 v[88:91], v[156:159], v[188:191], v[88:91]
	v_mfma_f32_16x16x32_bf16 v[80:83], v[148:151], v[196:199], v[80:83]
	v_mfma_f32_16x16x32_bf16 v[72:75], v[156:159], v[196:199], v[72:75]
	v_mfma_f32_16x16x32_bf16 v[124:127], v[152:155], v[176:179], v[124:127]
	v_mfma_f32_16x16x32_bf16 v[120:123], v[160:163], v[176:179], v[120:123]
	v_mfma_f32_16x16x32_bf16 v[116:119], v[152:155], v[184:187], v[116:119]
	v_mfma_f32_16x16x32_bf16 v[104:107], v[160:163], v[184:187], v[104:107]
	v_mfma_f32_16x16x32_bf16 v[96:99], v[152:155], v[192:195], v[96:99]
	v_mfma_f32_16x16x32_bf16 v[88:91], v[160:163], v[192:195], v[88:91]
	v_mfma_f32_16x16x32_bf16 v[80:83], v[152:155], v[200:203], v[80:83]
	v_mfma_f32_16x16x32_bf16 v[72:75], v[160:163], v[200:203], v[72:75]

	s_barrier
	s_add_i32 s26, 0, 0x1c000
	s_add_i32 s27, s54, s31


	s_mov_b32 m0, s27
	ds_read_b128 v[204:207], v147 offset:32768
	ds_read_b128 v[218:221], v147 offset:33792
	ds_read_b128 v[222:225], v147 offset:34816
	ds_read_b128 v[226:229], v147 offset:35840
	global_load_lds_dwordx4 v172, s[66:67]
	s_add_i32 m0, s27, 0x2000
	s_nop 0

	global_load_lds_dwordx4 v174, s[66:67]
	s_barrier
	s_waitcnt lgkmcnt(0)


	v_mfma_f32_16x16x32_bf16 v[112:115], v[204:207], v[164:167], v[112:115]
	v_mfma_f32_16x16x32_bf16 v[108:111], v[222:225], v[164:167], v[108:111]
	v_mfma_f32_16x16x32_bf16 v[100:103], v[204:207], v[180:183], v[100:103]
	v_mfma_f32_16x16x32_bf16 v[92:95], v[222:225], v[180:183], v[92:95]
	v_mfma_f32_16x16x32_bf16 v[84:87], v[204:207], v[188:191], v[84:87]
	v_mfma_f32_16x16x32_bf16 v[76:79], v[222:225], v[188:191], v[76:79]
	v_mfma_f32_16x16x32_bf16 v[68:71], v[204:207], v[196:199], v[68:71]
	v_mfma_f32_16x16x32_bf16 v[64:67], v[222:225], v[196:199], v[64:67]
	v_mfma_f32_16x16x32_bf16 v[112:115], v[218:221], v[176:179], v[112:115]
	v_mfma_f32_16x16x32_bf16 v[108:111], v[226:229], v[176:179], v[108:111]
	v_mfma_f32_16x16x32_bf16 v[100:103], v[218:221], v[184:187], v[100:103]
	v_mfma_f32_16x16x32_bf16 v[92:95], v[226:229], v[184:187], v[92:95]
	v_mfma_f32_16x16x32_bf16 v[84:87], v[218:221], v[192:195], v[84:87]
	v_mfma_f32_16x16x32_bf16 v[76:79], v[226:229], v[192:195], v[76:79]
	v_mfma_f32_16x16x32_bf16 v[68:71], v[218:221], v[200:203], v[68:71]
	v_mfma_f32_16x16x32_bf16 v[64:67], v[226:229], v[200:203], v[64:67]

	s_mov_b32 m0, s41

	s_barrier
	ds_read_b128 v[164:167], v145 offset:49152
	ds_read_b128 v[176:179], v145 offset:50176
	ds_read_b128 v[180:183], v145 offset:51200
	ds_read_b128 v[184:187], v145 offset:52224
	ds_read_b128 v[188:191], v145 offset:53248
	ds_read_b128 v[192:195], v145 offset:54272
	ds_read_b128 v[196:199], v145 offset:55296
	ds_read_b128 v[200:203], v145 offset:56320
	global_load_lds_dwordx4 v172, s[68:69]
	s_mov_b32 m0, s42
	s_nop 0

	global_load_lds_dwordx4 v174, s[68:69]
	s_barrier
	s_waitcnt lgkmcnt(0)


	v_mfma_f32_16x16x32_bf16 v[60:63], v[148:151], v[164:167], v[60:63]
	v_mfma_f32_16x16x32_bf16 v[56:59], v[156:159], v[164:167], v[56:59]
	v_mfma_f32_16x16x32_bf16 v[48:51], v[148:151], v[180:183], v[48:51]
	v_mfma_f32_16x16x32_bf16 v[40:43], v[156:159], v[180:183], v[40:43]
	v_mfma_f32_16x16x32_bf16 v[32:35], v[148:151], v[188:191], v[32:35]
	v_mfma_f32_16x16x32_bf16 v[24:27], v[156:159], v[188:191], v[24:27]
	v_mfma_f32_16x16x32_bf16 v[16:19], v[148:151], v[196:199], v[16:19]
	v_mfma_f32_16x16x32_bf16 v[8:11], v[156:159], v[196:199], v[8:11]
	v_mfma_f32_16x16x32_bf16 v[60:63], v[152:155], v[176:179], v[60:63]
	v_mfma_f32_16x16x32_bf16 v[56:59], v[160:163], v[176:179], v[56:59]
	v_mfma_f32_16x16x32_bf16 v[48:51], v[152:155], v[184:187], v[48:51]
	v_mfma_f32_16x16x32_bf16 v[40:43], v[160:163], v[184:187], v[40:43]
	v_mfma_f32_16x16x32_bf16 v[32:35], v[152:155], v[192:195], v[32:35]
	v_mfma_f32_16x16x32_bf16 v[24:27], v[160:163], v[192:195], v[24:27]
	v_mfma_f32_16x16x32_bf16 v[16:19], v[152:155], v[200:203], v[16:19]
	v_mfma_f32_16x16x32_bf16 v[8:11], v[160:163], v[200:203], v[8:11]

	s_barrier
	s_add_u32 s24, s24, 0x80080
	s_addc_u32 s25, s25, 0
	s_add_i32 s26, s26, s31
	s_mov_b32 m0, s26
	s_nop 0

	global_load_lds_dwordx4 v172, s[24:25]
	s_add_i32 m0, s26, 0x2000
	s_nop 0

	global_load_lds_dwordx4 v174, s[24:25]
	s_waitcnt vmcnt(6)
	s_barrier

	v_mfma_f32_16x16x32_bf16 v[52:55], v[204:207], v[164:167], v[52:55]
	v_mfma_f32_16x16x32_bf16 v[44:47], v[222:225], v[164:167], v[44:47]
	v_mfma_f32_16x16x32_bf16 v[36:39], v[204:207], v[180:183], v[36:39]
	v_mfma_f32_16x16x32_bf16 v[28:31], v[222:225], v[180:183], v[28:31]
	v_mfma_f32_16x16x32_bf16 v[20:23], v[204:207], v[188:191], v[20:23]
	v_mfma_f32_16x16x32_bf16 v[12:15], v[222:225], v[188:191], v[12:15]
	v_mfma_f32_16x16x32_bf16 v[4:7], v[204:207], v[196:199], v[4:7]
	v_mfma_f32_16x16x32_bf16 v[0:3], v[222:225], v[196:199], v[0:3]
	v_mfma_f32_16x16x32_bf16 v[52:55], v[218:221], v[176:179], v[52:55]
	v_mfma_f32_16x16x32_bf16 v[44:47], v[226:229], v[176:179], v[44:47]
	v_mfma_f32_16x16x32_bf16 v[36:39], v[218:221], v[184:187], v[36:39]
	v_mfma_f32_16x16x32_bf16 v[28:31], v[226:229], v[184:187], v[28:31]
	v_mfma_f32_16x16x32_bf16 v[20:23], v[218:221], v[192:195], v[20:23]
	v_mfma_f32_16x16x32_bf16 v[12:15], v[226:229], v[192:195], v[12:15]
	v_mfma_f32_16x16x32_bf16 v[4:7], v[218:221], v[200:203], v[4:7]
	v_mfma_f32_16x16x32_bf16 v[0:3], v[226:229], v[200:203], v[0:3]

	s_add_i32 s53, s53, 2
	s_add_u32 s22, s22, 0x100
	s_addc_u32 s23, s23, 0
	s_add_u32 s51, s51, 0x100
	s_addc_u32 s52, s52, 0
	s_cmp_gt_u32 s53, 29
	s_barrier
	s_cbranch_scc0 .LBB0_1167
	s_lshl_b32 s13, s20, 8
	v_mov_b32_e32 v138, v210
	v_mov_b32_e32 v142, v169
	s_add_i32 s13, s13, s39
	s_lshl_b32 s15, s48, 7
	v_add_u32_e32 v136, s13, v142
	v_ashrrev_i32_e32 v137, 31, v136
	v_lshl_add_u64 v[140:141], v[136:137], 2, s[2:3]
	global_load_dword v154, v[140:141], off
	global_load_dword v152, v[140:141], off offset:64
	v_lshl_add_u32 v138, v138, 4, v142
	v_and_b32_e32 v142, 3, v142
	v_ashrrev_i32_e32 v144, 2, v138
	v_and_b32_e32 v138, -4, v138
	v_lshl_or_b32 v146, v142, 2, s15
	v_add_u32_e32 v151, s13, v144
	v_lshl_add_u32 v149, v142, 6, v138
	v_or_b32_e32 v156, s40, v146
	global_load_dword v150, v[140:141], off offset:128
	global_load_dword v148, v[140:141], off offset:192
	global_load_dword v146, v[140:141], off offset:512
	global_load_dword v144, v[140:141], off offset:576
	global_load_dword v142, v[140:141], off offset:640
	global_load_dword v138, v[140:141], off offset:704
	v_mov_b64_e32 v[136:137], s[0:1]
	v_ashrrev_i32_e32 v157, 31, v156
	v_mad_i64_i32 v[158:159], s[22:23], v151, s47, v[136:137]
	v_lshlrev_b64 v[140:141], 1, v[156:157]
	v_lshl_add_u64 v[156:157], v[158:159], 0, v[140:141]
	v_add_u32_e32 v153, 16, v151
	s_and_b64 vcc, exec, s[4:5]
	s_mov_b32 s48, s12
	s_mov_b32 s20, s14
	s_mov_b64 s[24:25], s[18:19]
	s_waitcnt vmcnt(0)
	v_pk_mul_f32 v[126:127], v[126:127], v[154:155] op_sel_hi:[1,0]
	v_pk_mul_f32 v[124:125], v[124:125], v[154:155] op_sel_hi:[1,0]
	v_pk_mul_f32 v[114:115], v[114:115], v[154:155] op_sel_hi:[1,0]
	v_pk_mul_f32 v[112:113], v[112:113], v[154:155] op_sel_hi:[1,0]
	v_pk_mul_f32 v[122:123], v[122:123], v[154:155] op_sel_hi:[1,0]
	v_pk_mul_f32 v[120:121], v[120:121], v[154:155] op_sel_hi:[1,0]
	v_pk_mul_f32 v[110:111], v[110:111], v[154:155] op_sel_hi:[1,0]
	v_pk_mul_f32 v[108:109], v[108:109], v[154:155] op_sel_hi:[1,0]
	v_mul_f32_e32 v154, 0xbfb8aa3b, v124
	v_mul_f32_e32 v155, 0xbfb8aa3b, v125
	v_mul_f32_e32 v158, 0xbfb8aa3b, v126
	v_mul_f32_e32 v159, 0xbfb8aa3b, v127
	v_mul_f32_e32 v160, 0xbfb8aa3b, v120
	v_mul_f32_e32 v161, 0xbfb8aa3b, v121
	v_mul_f32_e32 v162, 0xbfb8aa3b, v122
	v_mul_f32_e32 v163, 0xbfb8aa3b, v123
	v_exp_f32_e32 v154, v154
	v_exp_f32_e32 v155, v155
	v_exp_f32_e32 v158, v158
	v_exp_f32_e32 v159, v159
	v_exp_f32_e32 v160, v160
	v_exp_f32_e32 v161, v161
	v_exp_f32_e32 v162, v162
	v_exp_f32_e32 v163, v163
	v_add_f32_e32 v154, 1.0, v154
	v_add_f32_e32 v155, 1.0, v155
	v_add_f32_e32 v158, 1.0, v158
	v_add_f32_e32 v159, 1.0, v159
	v_add_f32_e32 v160, 1.0, v160
	v_add_f32_e32 v161, 1.0, v161
	v_add_f32_e32 v162, 1.0, v162
	v_add_f32_e32 v163, 1.0, v163
	v_rcp_f32_e32 v154, v154
	v_rcp_f32_e32 v155, v155
	v_rcp_f32_e32 v158, v158
	v_rcp_f32_e32 v159, v159
	v_rcp_f32_e32 v160, v160
	v_rcp_f32_e32 v161, v161
	v_rcp_f32_e32 v162, v162
	v_rcp_f32_e32 v163, v163
	v_pk_mul_f32 v[124:125], v[124:125], v[154:155]
	v_pk_mul_f32 v[126:127], v[126:127], v[158:159]
	v_pk_mul_f32 v[120:121], v[120:121], v[160:161]
	v_pk_mul_f32 v[122:123], v[122:123], v[162:163]
	v_pk_mul_f32 v[112:113], v[112:113], v[124:125]
	v_pk_mul_f32 v[114:115], v[114:115], v[126:127]
	v_pk_mul_f32 v[118:119], v[118:119], v[152:153] op_sel_hi:[1,0]
	v_pk_mul_f32 v[116:117], v[116:117], v[152:153] op_sel_hi:[1,0]
	v_pk_mul_f32 v[108:109], v[108:109], v[120:121]
	v_pk_mul_f32 v[110:111], v[110:111], v[122:123]
	v_cvt_pk_bf16_f32 v112, v112, v113
	v_cvt_pk_bf16_f32 v113, v114, v115
	v_mul_f32_e32 v164, 0xbfb8aa3b, v116
	v_mul_f32_e32 v165, 0xbfb8aa3b, v117
	v_mul_f32_e32 v166, 0xbfb8aa3b, v118
	v_mul_f32_e32 v167, 0xbfb8aa3b, v119
	v_cvt_pk_bf16_f32 v114, v108, v109
	v_cvt_pk_bf16_f32 v111, v110, v111
	ds_bpermute_b32 v108, v149, v112
	ds_bpermute_b32 v109, v149, v113
	v_exp_f32_e32 v164, v164
	v_exp_f32_e32 v165, v165
	v_exp_f32_e32 v166, v166
	v_exp_f32_e32 v167, v167
	ds_bpermute_b32 v110, v149, v114
	ds_bpermute_b32 v111, v149, v111
	v_add_f32_e32 v164, 1.0, v164
	v_add_f32_e32 v113, 1.0, v165
	s_waitcnt lgkmcnt(0)
	global_store_dwordx2 v[156:157], v[108:109], off
	global_store_dwordx2 v[156:157], v[110:111], off offset:32
	v_add_f32_e32 v108, 1.0, v166
	v_add_f32_e32 v109, 1.0, v167
	v_rcp_f32_e32 v112, v164
	v_rcp_f32_e32 v113, v113
	v_rcp_f32_e32 v108, v108
	v_rcp_f32_e32 v109, v109
	v_pk_mul_f32 v[102:103], v[102:103], v[152:153] op_sel_hi:[1,0]
	v_pk_mul_f32 v[100:101], v[100:101], v[152:153] op_sel_hi:[1,0]
	v_pk_mul_f32 v[110:111], v[116:117], v[112:113]
	v_pk_mul_f32 v[108:109], v[118:119], v[108:109]
	v_pk_mul_f32 v[100:101], v[100:101], v[110:111]
	v_pk_mul_f32 v[102:103], v[102:103], v[108:109]
	v_cvt_pk_bf16_f32 v100, v100, v101
	v_cvt_pk_bf16_f32 v101, v102, v103
	v_pk_mul_f32 v[102:103], v[106:107], v[152:153] op_sel_hi:[1,0]
	v_pk_mul_f32 v[104:105], v[104:105], v[152:153] op_sel_hi:[1,0]
	v_mul_f32_e32 v108, 0xbfb8aa3b, v102
	v_mul_f32_e32 v106, 0xbfb8aa3b, v104
	v_mul_f32_e32 v107, 0xbfb8aa3b, v105
	v_mul_f32_e32 v109, 0xbfb8aa3b, v103
	v_exp_f32_e32 v106, v106
	v_exp_f32_e32 v107, v107
	v_exp_f32_e32 v108, v108
	v_exp_f32_e32 v109, v109
	v_add_f32_e32 v106, 1.0, v106
	v_add_f32_e32 v107, 1.0, v107
	v_add_f32_e32 v108, 1.0, v108
	v_add_f32_e32 v109, 1.0, v109
	v_rcp_f32_e32 v106, v106
	v_rcp_f32_e32 v107, v107
	v_rcp_f32_e32 v108, v108
	v_rcp_f32_e32 v109, v109
	v_pk_mul_f32 v[94:95], v[94:95], v[152:153] op_sel_hi:[1,0]
	v_pk_mul_f32 v[92:93], v[92:93], v[152:153] op_sel_hi:[1,0]
	v_pk_mul_f32 v[104:105], v[104:105], v[106:107]
	v_pk_mul_f32 v[102:103], v[102:103], v[108:109]
	v_pk_mul_f32 v[92:93], v[92:93], v[104:105]
	v_pk_mul_f32 v[94:95], v[94:95], v[102:103]
	ds_bpermute_b32 v100, v149, v100
	ds_bpermute_b32 v101, v149, v101
	v_cvt_pk_bf16_f32 v92, v92, v93
	v_cvt_pk_bf16_f32 v93, v94, v95
	ds_bpermute_b32 v92, v149, v92
	ds_bpermute_b32 v93, v149, v93
	v_mad_i64_i32 v[94:95], s[22:23], v153, s47, v[136:137]
	v_lshl_add_u64 v[94:95], v[94:95], 0, v[140:141]
	s_waitcnt lgkmcnt(2)
	global_store_dwordx2 v[94:95], v[100:101], off
	s_waitcnt lgkmcnt(0)
	global_store_dwordx2 v[94:95], v[92:93], off offset:32
	v_pk_mul_f32 v[92:93], v[98:99], v[150:151] op_sel_hi:[1,0]
	v_pk_mul_f32 v[94:95], v[96:97], v[150:151] op_sel_hi:[1,0]
	v_mul_f32_e32 v98, 0xbfb8aa3b, v92
	v_mul_f32_e32 v96, 0xbfb8aa3b, v94
	v_mul_f32_e32 v97, 0xbfb8aa3b, v95
	v_mul_f32_e32 v99, 0xbfb8aa3b, v93
	v_exp_f32_e32 v96, v96
	v_exp_f32_e32 v97, v97
	v_exp_f32_e32 v98, v98
	v_exp_f32_e32 v99, v99
	v_add_f32_e32 v96, 1.0, v96
	v_add_f32_e32 v97, 1.0, v97
	v_add_f32_e32 v98, 1.0, v98
	v_add_f32_e32 v99, 1.0, v99
	v_rcp_f32_e32 v96, v96
	v_rcp_f32_e32 v97, v97
	v_rcp_f32_e32 v98, v98
	v_rcp_f32_e32 v99, v99
	v_pk_mul_f32 v[86:87], v[86:87], v[150:151] op_sel_hi:[1,0]
	v_pk_mul_f32 v[84:85], v[84:85], v[150:151] op_sel_hi:[1,0]
	v_pk_mul_f32 v[94:95], v[94:95], v[96:97]
	v_pk_mul_f32 v[92:93], v[92:93], v[98:99]
	v_pk_mul_f32 v[84:85], v[84:85], v[94:95]
	v_pk_mul_f32 v[86:87], v[86:87], v[92:93]
	v_cvt_pk_bf16_f32 v84, v84, v85
	v_cvt_pk_bf16_f32 v85, v86, v87
	v_pk_mul_f32 v[86:87], v[90:91], v[150:151] op_sel_hi:[1,0]
	v_pk_mul_f32 v[88:89], v[88:89], v[150:151] op_sel_hi:[1,0]
	v_mul_f32_e32 v92, 0xbfb8aa3b, v86
	v_mul_f32_e32 v90, 0xbfb8aa3b, v88
	v_mul_f32_e32 v91, 0xbfb8aa3b, v89
	v_mul_f32_e32 v93, 0xbfb8aa3b, v87
	v_exp_f32_e32 v90, v90
	v_exp_f32_e32 v91, v91
	v_exp_f32_e32 v92, v92
	v_exp_f32_e32 v93, v93
	v_add_f32_e32 v90, 1.0, v90
	v_add_f32_e32 v91, 1.0, v91
	v_add_f32_e32 v92, 1.0, v92
	v_add_f32_e32 v93, 1.0, v93
	v_rcp_f32_e32 v90, v90
	v_rcp_f32_e32 v91, v91
	v_rcp_f32_e32 v92, v92
	v_rcp_f32_e32 v93, v93
	v_pk_mul_f32 v[78:79], v[78:79], v[150:151] op_sel_hi:[1,0]
	v_pk_mul_f32 v[76:77], v[76:77], v[150:151] op_sel_hi:[1,0]
	v_pk_mul_f32 v[88:89], v[88:89], v[90:91]
	v_pk_mul_f32 v[86:87], v[86:87], v[92:93]
	v_pk_mul_f32 v[76:77], v[76:77], v[88:89]
	v_pk_mul_f32 v[78:79], v[78:79], v[86:87]
	ds_bpermute_b32 v84, v149, v84
	ds_bpermute_b32 v85, v149, v85
	v_cvt_pk_bf16_f32 v76, v76, v77
	v_cvt_pk_bf16_f32 v77, v78, v79
	ds_bpermute_b32 v76, v149, v76
	ds_bpermute_b32 v77, v149, v77
	v_add_u32_e32 v100, 32, v151
	v_mad_i64_i32 v[78:79], s[22:23], v100, s47, v[136:137]
	v_lshl_add_u64 v[78:79], v[78:79], 0, v[140:141]
	s_waitcnt lgkmcnt(2)
	global_store_dwordx2 v[78:79], v[84:85], off
	s_waitcnt lgkmcnt(0)
	global_store_dwordx2 v[78:79], v[76:77], off offset:32
	v_pk_mul_f32 v[76:77], v[82:83], v[148:149] op_sel_hi:[1,0]
	v_pk_mul_f32 v[78:79], v[80:81], v[148:149] op_sel_hi:[1,0]
	v_mul_f32_e32 v82, 0xbfb8aa3b, v76
	v_mul_f32_e32 v80, 0xbfb8aa3b, v78
	v_mul_f32_e32 v81, 0xbfb8aa3b, v79
	v_mul_f32_e32 v83, 0xbfb8aa3b, v77
	v_exp_f32_e32 v80, v80
	v_exp_f32_e32 v81, v81
	v_exp_f32_e32 v82, v82
	v_exp_f32_e32 v83, v83
	v_add_f32_e32 v80, 1.0, v80
	v_add_f32_e32 v81, 1.0, v81
	v_add_f32_e32 v82, 1.0, v82
	v_add_f32_e32 v83, 1.0, v83
	v_rcp_f32_e32 v80, v80
	v_rcp_f32_e32 v81, v81
	v_rcp_f32_e32 v82, v82
	v_rcp_f32_e32 v83, v83
	v_pk_mul_f32 v[70:71], v[70:71], v[148:149] op_sel_hi:[1,0]
	v_pk_mul_f32 v[68:69], v[68:69], v[148:149] op_sel_hi:[1,0]
	v_pk_mul_f32 v[78:79], v[78:79], v[80:81]
	v_pk_mul_f32 v[76:77], v[76:77], v[82:83]
	v_pk_mul_f32 v[68:69], v[68:69], v[78:79]
	v_pk_mul_f32 v[70:71], v[70:71], v[76:77]
	v_cvt_pk_bf16_f32 v68, v68, v69
	v_cvt_pk_bf16_f32 v69, v70, v71
	v_pk_mul_f32 v[70:71], v[74:75], v[148:149] op_sel_hi:[1,0]
	v_pk_mul_f32 v[72:73], v[72:73], v[148:149] op_sel_hi:[1,0]
	v_mul_f32_e32 v76, 0xbfb8aa3b, v70
	v_mul_f32_e32 v74, 0xbfb8aa3b, v72
	v_mul_f32_e32 v75, 0xbfb8aa3b, v73
	v_mul_f32_e32 v77, 0xbfb8aa3b, v71
	v_exp_f32_e32 v74, v74
	v_exp_f32_e32 v75, v75
	v_exp_f32_e32 v76, v76
	v_exp_f32_e32 v77, v77
	v_add_f32_e32 v74, 1.0, v74
	v_add_f32_e32 v75, 1.0, v75
	v_add_f32_e32 v76, 1.0, v76
	v_add_f32_e32 v77, 1.0, v77
	v_rcp_f32_e32 v74, v74
	v_rcp_f32_e32 v75, v75
	v_rcp_f32_e32 v76, v76
	v_rcp_f32_e32 v77, v77
	v_pk_mul_f32 v[66:67], v[66:67], v[148:149] op_sel_hi:[1,0]
	v_pk_mul_f32 v[64:65], v[64:65], v[148:149] op_sel_hi:[1,0]
	v_pk_mul_f32 v[72:73], v[72:73], v[74:75]
	v_pk_mul_f32 v[70:71], v[70:71], v[76:77]
	v_pk_mul_f32 v[64:65], v[64:65], v[72:73]
	v_pk_mul_f32 v[66:67], v[66:67], v[70:71]
	ds_bpermute_b32 v68, v149, v68
	ds_bpermute_b32 v69, v149, v69
	v_cvt_pk_bf16_f32 v64, v64, v65
	v_cvt_pk_bf16_f32 v65, v66, v67
	ds_bpermute_b32 v64, v149, v64
	ds_bpermute_b32 v65, v149, v65
	v_add_u32_e32 v84, 48, v151
	v_mad_i64_i32 v[66:67], s[22:23], v84, s47, v[136:137]
	v_lshl_add_u64 v[66:67], v[66:67], 0, v[140:141]
	v_pk_mul_f32 v[60:61], v[60:61], v[146:147] op_sel_hi:[1,0]
	s_waitcnt lgkmcnt(2)
	global_store_dwordx2 v[66:67], v[68:69], off
	s_waitcnt lgkmcnt(0)
	global_store_dwordx2 v[66:67], v[64:65], off offset:32
	v_pk_mul_f32 v[62:63], v[62:63], v[146:147] op_sel_hi:[1,0]
	v_mul_f32_e32 v64, 0xbfb8aa3b, v60
	v_mul_f32_e32 v65, 0xbfb8aa3b, v61
	v_exp_f32_e32 v64, v64
	v_exp_f32_e32 v65, v65
	v_mul_f32_e32 v66, 0xbfb8aa3b, v62
	v_mul_f32_e32 v67, 0xbfb8aa3b, v63
	v_exp_f32_e32 v66, v66
	v_exp_f32_e32 v67, v67
	v_add_f32_e32 v64, 1.0, v64
	v_add_f32_e32 v65, 1.0, v65
	v_rcp_f32_e32 v64, v64
	v_rcp_f32_e32 v65, v65
	v_add_f32_e32 v66, 1.0, v66
	v_add_f32_e32 v67, 1.0, v67
	v_rcp_f32_e32 v66, v66
	v_rcp_f32_e32 v67, v67
	v_pk_mul_f32 v[52:53], v[52:53], v[146:147] op_sel_hi:[1,0]
	v_pk_mul_f32 v[60:61], v[60:61], v[64:65]
	v_pk_mul_f32 v[54:55], v[54:55], v[146:147] op_sel_hi:[1,0]
	v_pk_mul_f32 v[52:53], v[52:53], v[60:61]
	v_pk_mul_f32 v[60:61], v[62:63], v[66:67]
	v_cvt_pk_bf16_f32 v52, v52, v53
	v_pk_mul_f32 v[54:55], v[54:55], v[60:61]
	v_pk_mul_f32 v[56:57], v[56:57], v[146:147] op_sel_hi:[1,0]
	v_cvt_pk_bf16_f32 v53, v54, v55
	v_pk_mul_f32 v[54:55], v[58:59], v[146:147] op_sel_hi:[1,0]
	v_mul_f32_e32 v58, 0xbfb8aa3b, v56
	v_mul_f32_e32 v59, 0xbfb8aa3b, v57
	v_mul_f32_e32 v60, 0xbfb8aa3b, v54
	v_mul_f32_e32 v61, 0xbfb8aa3b, v55
	v_exp_f32_e32 v58, v58
	v_exp_f32_e32 v59, v59
	v_exp_f32_e32 v60, v60
	v_exp_f32_e32 v61, v61
	v_add_f32_e32 v58, 1.0, v58
	v_add_f32_e32 v59, 1.0, v59
	v_add_f32_e32 v60, 1.0, v60
	v_add_f32_e32 v61, 1.0, v61
	v_rcp_f32_e32 v58, v58
	v_rcp_f32_e32 v59, v59
	v_rcp_f32_e32 v60, v60
	v_rcp_f32_e32 v61, v61
	v_pk_mul_f32 v[46:47], v[46:47], v[146:147] op_sel_hi:[1,0]
	v_pk_mul_f32 v[44:45], v[44:45], v[146:147] op_sel_hi:[1,0]
	v_pk_mul_f32 v[56:57], v[56:57], v[58:59]
	v_pk_mul_f32 v[54:55], v[54:55], v[60:61]
	v_pk_mul_f32 v[44:45], v[44:45], v[56:57]
	v_pk_mul_f32 v[46:47], v[46:47], v[54:55]
	ds_bpermute_b32 v52, v149, v52
	ds_bpermute_b32 v53, v149, v53
	v_cvt_pk_bf16_f32 v44, v44, v45
	v_cvt_pk_bf16_f32 v45, v46, v47
	ds_bpermute_b32 v44, v149, v44
	ds_bpermute_b32 v45, v149, v45
	v_add_u32_e32 v68, 0x80, v151
	v_mad_i64_i32 v[46:47], s[22:23], v68, s47, v[136:137]
	v_lshl_add_u64 v[46:47], v[46:47], 0, v[140:141]
	s_waitcnt lgkmcnt(2)
	global_store_dwordx2 v[46:47], v[52:53], off
	s_waitcnt lgkmcnt(0)
	global_store_dwordx2 v[46:47], v[44:45], off offset:32
	v_pk_mul_f32 v[44:45], v[50:51], v[144:145] op_sel_hi:[1,0]
	v_pk_mul_f32 v[46:47], v[48:49], v[144:145] op_sel_hi:[1,0]
	v_mul_f32_e32 v50, 0xbfb8aa3b, v44
	v_mul_f32_e32 v48, 0xbfb8aa3b, v46
	v_mul_f32_e32 v49, 0xbfb8aa3b, v47
	v_mul_f32_e32 v51, 0xbfb8aa3b, v45
	v_exp_f32_e32 v48, v48
	v_exp_f32_e32 v49, v49
	v_exp_f32_e32 v50, v50
	v_exp_f32_e32 v51, v51
	v_add_f32_e32 v48, 1.0, v48
	v_add_f32_e32 v49, 1.0, v49
	v_add_f32_e32 v50, 1.0, v50
	v_add_f32_e32 v51, 1.0, v51
	v_rcp_f32_e32 v48, v48
	v_rcp_f32_e32 v49, v49
	v_rcp_f32_e32 v50, v50
	v_rcp_f32_e32 v51, v51
	v_pk_mul_f32 v[38:39], v[38:39], v[144:145] op_sel_hi:[1,0]
	v_pk_mul_f32 v[36:37], v[36:37], v[144:145] op_sel_hi:[1,0]
	v_pk_mul_f32 v[46:47], v[46:47], v[48:49]
	v_pk_mul_f32 v[44:45], v[44:45], v[50:51]
	v_pk_mul_f32 v[36:37], v[36:37], v[46:47]
	v_pk_mul_f32 v[38:39], v[38:39], v[44:45]
	v_cvt_pk_bf16_f32 v36, v36, v37
	v_cvt_pk_bf16_f32 v37, v38, v39
	v_pk_mul_f32 v[38:39], v[42:43], v[144:145] op_sel_hi:[1,0]
	v_pk_mul_f32 v[40:41], v[40:41], v[144:145] op_sel_hi:[1,0]
	v_mul_f32_e32 v44, 0xbfb8aa3b, v38
	v_mul_f32_e32 v42, 0xbfb8aa3b, v40
	v_mul_f32_e32 v43, 0xbfb8aa3b, v41
	v_mul_f32_e32 v45, 0xbfb8aa3b, v39
	v_exp_f32_e32 v42, v42
	v_exp_f32_e32 v43, v43
	v_exp_f32_e32 v44, v44
	v_exp_f32_e32 v45, v45
	v_add_f32_e32 v42, 1.0, v42
	v_add_f32_e32 v43, 1.0, v43
	v_add_f32_e32 v44, 1.0, v44
	v_add_f32_e32 v45, 1.0, v45
	v_rcp_f32_e32 v42, v42
	v_rcp_f32_e32 v43, v43
	v_rcp_f32_e32 v44, v44
	v_rcp_f32_e32 v45, v45
	v_pk_mul_f32 v[30:31], v[30:31], v[144:145] op_sel_hi:[1,0]
	v_pk_mul_f32 v[28:29], v[28:29], v[144:145] op_sel_hi:[1,0]
	v_pk_mul_f32 v[40:41], v[40:41], v[42:43]
	v_pk_mul_f32 v[38:39], v[38:39], v[44:45]
	v_pk_mul_f32 v[28:29], v[28:29], v[40:41]
	v_pk_mul_f32 v[30:31], v[30:31], v[38:39]
	ds_bpermute_b32 v36, v149, v36
	ds_bpermute_b32 v37, v149, v37
	v_cvt_pk_bf16_f32 v28, v28, v29
	v_cvt_pk_bf16_f32 v29, v30, v31
	ds_bpermute_b32 v28, v149, v28
	ds_bpermute_b32 v29, v149, v29
	v_add_u32_e32 v52, 0x90, v151
	v_mad_i64_i32 v[30:31], s[22:23], v52, s47, v[136:137]
	v_lshl_add_u64 v[30:31], v[30:31], 0, v[140:141]
	s_waitcnt lgkmcnt(2)
	global_store_dwordx2 v[30:31], v[36:37], off
	s_waitcnt lgkmcnt(0)
	global_store_dwordx2 v[30:31], v[28:29], off offset:32
	v_pk_mul_f32 v[28:29], v[34:35], v[142:143] op_sel_hi:[1,0]
	v_pk_mul_f32 v[30:31], v[32:33], v[142:143] op_sel_hi:[1,0]
	v_mul_f32_e32 v34, 0xbfb8aa3b, v28
	v_mul_f32_e32 v32, 0xbfb8aa3b, v30
	v_mul_f32_e32 v33, 0xbfb8aa3b, v31
	v_mul_f32_e32 v35, 0xbfb8aa3b, v29
	v_exp_f32_e32 v32, v32
	v_exp_f32_e32 v33, v33
	v_exp_f32_e32 v34, v34
	v_exp_f32_e32 v35, v35
	v_add_f32_e32 v32, 1.0, v32
	v_add_f32_e32 v33, 1.0, v33
	v_add_f32_e32 v34, 1.0, v34
	v_add_f32_e32 v35, 1.0, v35
	v_rcp_f32_e32 v32, v32
	v_rcp_f32_e32 v33, v33
	v_rcp_f32_e32 v34, v34
	v_rcp_f32_e32 v35, v35
	v_pk_mul_f32 v[22:23], v[22:23], v[142:143] op_sel_hi:[1,0]
	v_pk_mul_f32 v[20:21], v[20:21], v[142:143] op_sel_hi:[1,0]
	v_pk_mul_f32 v[30:31], v[30:31], v[32:33]
	v_pk_mul_f32 v[28:29], v[28:29], v[34:35]
	v_pk_mul_f32 v[20:21], v[20:21], v[30:31]
	v_pk_mul_f32 v[22:23], v[22:23], v[28:29]
	v_cvt_pk_bf16_f32 v20, v20, v21
	v_cvt_pk_bf16_f32 v21, v22, v23
	v_pk_mul_f32 v[22:23], v[26:27], v[142:143] op_sel_hi:[1,0]
	v_pk_mul_f32 v[24:25], v[24:25], v[142:143] op_sel_hi:[1,0]
	v_mul_f32_e32 v28, 0xbfb8aa3b, v22
	v_mul_f32_e32 v26, 0xbfb8aa3b, v24
	v_mul_f32_e32 v27, 0xbfb8aa3b, v25
	v_mul_f32_e32 v29, 0xbfb8aa3b, v23
	v_exp_f32_e32 v26, v26
	v_exp_f32_e32 v27, v27
	v_exp_f32_e32 v28, v28
	v_exp_f32_e32 v29, v29
	v_add_f32_e32 v26, 1.0, v26
	v_add_f32_e32 v27, 1.0, v27
	v_add_f32_e32 v28, 1.0, v28
	v_add_f32_e32 v29, 1.0, v29
	v_rcp_f32_e32 v26, v26
	v_rcp_f32_e32 v27, v27
	v_rcp_f32_e32 v28, v28
	v_rcp_f32_e32 v29, v29
	v_pk_mul_f32 v[14:15], v[14:15], v[142:143] op_sel_hi:[1,0]
	v_pk_mul_f32 v[12:13], v[12:13], v[142:143] op_sel_hi:[1,0]
	v_pk_mul_f32 v[24:25], v[24:25], v[26:27]
	v_pk_mul_f32 v[22:23], v[22:23], v[28:29]
	v_pk_mul_f32 v[12:13], v[12:13], v[24:25]
	v_pk_mul_f32 v[14:15], v[14:15], v[22:23]
	ds_bpermute_b32 v20, v149, v20
	ds_bpermute_b32 v21, v149, v21
	v_cvt_pk_bf16_f32 v12, v12, v13
	v_cvt_pk_bf16_f32 v13, v14, v15
	ds_bpermute_b32 v12, v149, v12
	ds_bpermute_b32 v13, v149, v13
	v_add_u32_e32 v36, 0xa0, v151
	v_mad_i64_i32 v[14:15], s[22:23], v36, s47, v[136:137]
	v_lshl_add_u64 v[14:15], v[14:15], 0, v[140:141]
	s_waitcnt lgkmcnt(2)
	global_store_dwordx2 v[14:15], v[20:21], off
	s_waitcnt lgkmcnt(0)
	global_store_dwordx2 v[14:15], v[12:13], off offset:32
	v_pk_mul_f32 v[12:13], v[18:19], v[138:139] op_sel_hi:[1,0]
	v_pk_mul_f32 v[14:15], v[16:17], v[138:139] op_sel_hi:[1,0]
	v_mul_f32_e32 v18, 0xbfb8aa3b, v12
	v_mul_f32_e32 v16, 0xbfb8aa3b, v14
	v_mul_f32_e32 v17, 0xbfb8aa3b, v15
	v_mul_f32_e32 v19, 0xbfb8aa3b, v13
	v_exp_f32_e32 v16, v16
	v_exp_f32_e32 v17, v17
	v_exp_f32_e32 v18, v18
	v_exp_f32_e32 v19, v19
	v_add_f32_e32 v16, 1.0, v16
	v_add_f32_e32 v17, 1.0, v17
	v_add_f32_e32 v18, 1.0, v18
	v_add_f32_e32 v19, 1.0, v19
	v_rcp_f32_e32 v16, v16
	v_rcp_f32_e32 v17, v17
	v_rcp_f32_e32 v18, v18
	v_rcp_f32_e32 v19, v19
	v_pk_mul_f32 v[6:7], v[6:7], v[138:139] op_sel_hi:[1,0]
	v_pk_mul_f32 v[4:5], v[4:5], v[138:139] op_sel_hi:[1,0]
	v_pk_mul_f32 v[14:15], v[14:15], v[16:17]
	v_pk_mul_f32 v[12:13], v[12:13], v[18:19]
	v_pk_mul_f32 v[4:5], v[4:5], v[14:15]
	v_pk_mul_f32 v[6:7], v[6:7], v[12:13]
	v_cvt_pk_bf16_f32 v4, v4, v5
	v_cvt_pk_bf16_f32 v5, v6, v7
	v_pk_mul_f32 v[6:7], v[10:11], v[138:139] op_sel_hi:[1,0]
	v_pk_mul_f32 v[8:9], v[8:9], v[138:139] op_sel_hi:[1,0]
	v_mul_f32_e32 v12, 0xbfb8aa3b, v6
	v_mul_f32_e32 v10, 0xbfb8aa3b, v8
	v_mul_f32_e32 v11, 0xbfb8aa3b, v9
	v_mul_f32_e32 v13, 0xbfb8aa3b, v7
	v_exp_f32_e32 v10, v10
	v_exp_f32_e32 v11, v11
	v_exp_f32_e32 v12, v12
	v_exp_f32_e32 v13, v13
	v_add_f32_e32 v10, 1.0, v10
	v_add_f32_e32 v11, 1.0, v11
	v_add_f32_e32 v12, 1.0, v12
	v_add_f32_e32 v13, 1.0, v13
	v_rcp_f32_e32 v10, v10
	v_rcp_f32_e32 v11, v11
	v_rcp_f32_e32 v12, v12
	v_rcp_f32_e32 v13, v13
	v_pk_mul_f32 v[2:3], v[2:3], v[138:139] op_sel_hi:[1,0]
	v_pk_mul_f32 v[0:1], v[0:1], v[138:139] op_sel_hi:[1,0]
	v_pk_mul_f32 v[8:9], v[8:9], v[10:11]
	v_pk_mul_f32 v[6:7], v[6:7], v[12:13]
	v_pk_mul_f32 v[0:1], v[0:1], v[8:9]
	v_pk_mul_f32 v[2:3], v[2:3], v[6:7]
	ds_bpermute_b32 v4, v149, v4
	ds_bpermute_b32 v5, v149, v5
	v_cvt_pk_bf16_f32 v0, v0, v1
	v_cvt_pk_bf16_f32 v1, v2, v3
	ds_bpermute_b32 v0, v149, v0
	ds_bpermute_b32 v1, v149, v1
	v_add_u32_e32 v20, 0xb0, v151
	v_mad_i64_i32 v[2:3], s[22:23], v20, s47, v[136:137]
	v_lshl_add_u64 v[2:3], v[2:3], 0, v[140:141]
	s_mov_b64 s[22:23], s[16:17]
	s_waitcnt lgkmcnt(2)
	global_store_dwordx2 v[2:3], v[4:5], off
	s_waitcnt lgkmcnt(0)
	global_store_dwordx2 v[2:3], v[0:1], off offset:32
	s_cbranch_vccz .LBB0_1164
	s_waitcnt vmcnt(0)
	s_cmpk_gt_u32 s28, 0xff
	s_cbranch_scc1 .LBB0_1171
	s_barrier

.LBB0_1258:
	ds_read_b128 v[128:131], v159
	ds_read_b128 v[132:135], v159 offset:1024
	ds_read_b128 v[136:139], v159 offset:2048
	ds_read_b128 v[150:153], v159 offset:3072
	s_add_i32 s54, s18, 2
	s_add_u32 s19, s16, 0xffea0080
	s_addc_u32 s20, s17, -1
	s_cmp_eq_u32 s13, s18
	s_cselect_b32 s18, s4, s52
	s_cselect_b32 s21, s15, s20
	s_cselect_b32 s20, s14, s19
	s_cselect_b32 s19, s5, s53

	s_add_i32 m0, s26, 0xc000
	ds_read_b128 v[154:157], v160
	ds_read_b128 v[162:165], v160 offset:1024
	ds_read_b128 v[172:175], v160 offset:2048
	ds_read_b128 v[176:179], v160 offset:3072
	ds_read_b128 v[180:183], v160 offset:4096
	ds_read_b128 v[184:187], v160 offset:5120
	ds_read_b128 v[188:191], v160 offset:6144
	ds_read_b128 v[192:195], v160 offset:7168
	global_load_lds_dwordx4 v146, s[16:17]
	s_add_i32 m0, s26, 0xe000
	s_nop 0

	global_load_lds_dwordx4 v148, s[16:17]
	s_waitcnt lgkmcnt(8)
	s_barrier
	s_waitcnt lgkmcnt(0)


	v_mfma_f32_16x16x32_bf16 v[124:127], v[128:131], v[154:157], v[124:127]
	v_mfma_f32_16x16x32_bf16 v[120:123], v[136:139], v[154:157], v[120:123]
	v_mfma_f32_16x16x32_bf16 v[116:119], v[128:131], v[172:175], v[116:119]
	v_mfma_f32_16x16x32_bf16 v[104:107], v[136:139], v[172:175], v[104:107]
	v_mfma_f32_16x16x32_bf16 v[96:99], v[128:131], v[180:183], v[96:99]
	v_mfma_f32_16x16x32_bf16 v[88:91], v[136:139], v[180:183], v[88:91]
	v_mfma_f32_16x16x32_bf16 v[80:83], v[128:131], v[188:191], v[80:83]
	v_mfma_f32_16x16x32_bf16 v[72:75], v[136:139], v[188:191], v[72:75]
	v_mfma_f32_16x16x32_bf16 v[124:127], v[132:135], v[162:165], v[124:127]
	v_mfma_f32_16x16x32_bf16 v[120:123], v[150:153], v[162:165], v[120:123]
	v_mfma_f32_16x16x32_bf16 v[116:119], v[132:135], v[176:179], v[116:119]
	v_mfma_f32_16x16x32_bf16 v[104:107], v[150:153], v[176:179], v[104:107]
	v_mfma_f32_16x16x32_bf16 v[96:99], v[132:135], v[184:187], v[96:99]
	v_mfma_f32_16x16x32_bf16 v[88:91], v[150:153], v[184:187], v[88:91]
	v_mfma_f32_16x16x32_bf16 v[80:83], v[132:135], v[192:195], v[80:83]
	v_mfma_f32_16x16x32_bf16 v[72:75], v[150:153], v[192:195], v[72:75]

	s_barrier
	s_add_i32 s55, s35, s25
	s_add_u32 s66, s18, s6
	s_addc_u32 s67, s19, s7
	s_mov_b32 m0, s55
	ds_read_b128 v[196:199], v161
	ds_read_b128 v[200:203], v161 offset:1024
	ds_read_b128 v[204:207], v161 offset:2048
	ds_read_b128 v[212:215], v161 offset:3072
	global_load_lds_dwordx4 v140, s[18:19]
	s_add_i32 m0, s55, 0x2000
	s_nop 0

	global_load_lds_dwordx4 v142, s[18:19]
	s_barrier
	s_waitcnt lgkmcnt(0)


	v_mfma_f32_16x16x32_bf16 v[112:115], v[196:199], v[154:157], v[112:115]
	v_mfma_f32_16x16x32_bf16 v[108:111], v[204:207], v[154:157], v[108:111]
	v_mfma_f32_16x16x32_bf16 v[100:103], v[196:199], v[172:175], v[100:103]
	v_mfma_f32_16x16x32_bf16 v[92:95], v[204:207], v[172:175], v[92:95]
	v_mfma_f32_16x16x32_bf16 v[84:87], v[196:199], v[180:183], v[84:87]
	v_mfma_f32_16x16x32_bf16 v[76:79], v[204:207], v[180:183], v[76:79]
	v_mfma_f32_16x16x32_bf16 v[68:71], v[196:199], v[188:191], v[68:71]
	v_mfma_f32_16x16x32_bf16 v[64:67], v[204:207], v[188:191], v[64:67]
	v_mfma_f32_16x16x32_bf16 v[112:115], v[200:203], v[162:165], v[112:115]
	v_mfma_f32_16x16x32_bf16 v[108:111], v[212:215], v[162:165], v[108:111]
	v_mfma_f32_16x16x32_bf16 v[100:103], v[200:203], v[176:179], v[100:103]
	v_mfma_f32_16x16x32_bf16 v[92:95], v[212:215], v[176:179], v[92:95]
	v_mfma_f32_16x16x32_bf16 v[84:87], v[200:203], v[184:187], v[84:87]
	v_mfma_f32_16x16x32_bf16 v[76:79], v[212:215], v[184:187], v[76:79]
	v_mfma_f32_16x16x32_bf16 v[68:71], v[200:203], v[192:195], v[68:71]
	v_mfma_f32_16x16x32_bf16 v[64:67], v[212:215], v[192:195], v[64:67]

	s_mov_b32 m0, s26
	s_add_u32 s68, s20, s6
	s_addc_u32 s69, s21, s7
	s_barrier
	ds_read_b128 v[154:157], v160 offset:16384
	ds_read_b128 v[162:165], v160 offset:17408
	ds_read_b128 v[172:175], v160 offset:18432
	ds_read_b128 v[176:179], v160 offset:19456
	ds_read_b128 v[180:183], v160 offset:20480
	ds_read_b128 v[184:187], v160 offset:21504
	ds_read_b128 v[188:191], v160 offset:22528
	ds_read_b128 v[192:195], v160 offset:23552
	global_load_lds_dwordx4 v140, s[20:21]
	s_mov_b32 m0, s27
	s_nop 0

	global_load_lds_dwordx4 v142, s[20:21]
	s_barrier
	s_waitcnt lgkmcnt(0)


	v_mfma_f32_16x16x32_bf16 v[60:63], v[128:131], v[154:157], v[60:63]
	v_mfma_f32_16x16x32_bf16 v[56:59], v[136:139], v[154:157], v[56:59]
	v_mfma_f32_16x16x32_bf16 v[52:55], v[128:131], v[172:175], v[52:55]
	v_mfma_f32_16x16x32_bf16 v[40:43], v[136:139], v[172:175], v[40:43]
	v_mfma_f32_16x16x32_bf16 v[36:39], v[128:131], v[180:183], v[36:39]
	v_mfma_f32_16x16x32_bf16 v[24:27], v[136:139], v[180:183], v[24:27]
	v_mfma_f32_16x16x32_bf16 v[20:23], v[128:131], v[188:191], v[20:23]
	v_mfma_f32_16x16x32_bf16 v[8:11], v[136:139], v[188:191], v[8:11]
	v_mfma_f32_16x16x32_bf16 v[60:63], v[132:135], v[162:165], v[60:63]
	v_mfma_f32_16x16x32_bf16 v[56:59], v[150:153], v[162:165], v[56:59]
	v_mfma_f32_16x16x32_bf16 v[52:55], v[132:135], v[176:179], v[52:55]
	v_mfma_f32_16x16x32_bf16 v[40:43], v[150:153], v[176:179], v[40:43]
	v_mfma_f32_16x16x32_bf16 v[36:39], v[132:135], v[184:187], v[36:39]
	v_mfma_f32_16x16x32_bf16 v[24:27], v[150:153], v[184:187], v[24:27]
	v_mfma_f32_16x16x32_bf16 v[20:23], v[132:135], v[192:195], v[20:23]
	v_mfma_f32_16x16x32_bf16 v[8:11], v[150:153], v[192:195], v[8:11]

	s_barrier
	s_add_u32 s56, s18, 0x160000
	s_addc_u32 s57, s19, 0
	s_add_i32 s55, s36, s25
	s_mov_b32 m0, s55
	s_nop 0

	global_load_lds_dwordx4 v140, s[56:57]
	s_add_i32 m0, s55, 0x2000
	s_nop 0

	global_load_lds_dwordx4 v142, s[56:57]
	s_waitcnt vmcnt(6)
	s_barrier

	v_mfma_f32_16x16x32_bf16 v[48:51], v[196:199], v[154:157], v[48:51]
	v_mfma_f32_16x16x32_bf16 v[44:47], v[204:207], v[154:157], v[44:47]
	v_mfma_f32_16x16x32_bf16 v[32:35], v[196:199], v[172:175], v[32:35]
	v_mfma_f32_16x16x32_bf16 v[28:31], v[204:207], v[172:175], v[28:31]
	v_mfma_f32_16x16x32_bf16 v[16:19], v[196:199], v[180:183], v[16:19]
	v_mfma_f32_16x16x32_bf16 v[12:15], v[204:207], v[180:183], v[12:15]
	v_mfma_f32_16x16x32_bf16 v[4:7], v[196:199], v[188:191], v[4:7]
	v_mfma_f32_16x16x32_bf16 v[0:3], v[204:207], v[188:191], v[0:3]
	v_mfma_f32_16x16x32_bf16 v[48:51], v[200:203], v[162:165], v[48:51]
	v_mfma_f32_16x16x32_bf16 v[44:47], v[212:215], v[162:165], v[44:47]
	v_mfma_f32_16x16x32_bf16 v[32:35], v[200:203], v[176:179], v[32:35]
	v_mfma_f32_16x16x32_bf16 v[28:31], v[212:215], v[176:179], v[28:31]
	v_mfma_f32_16x16x32_bf16 v[16:19], v[200:203], v[184:187], v[16:19]
	v_mfma_f32_16x16x32_bf16 v[12:15], v[212:215], v[184:187], v[12:15]
	v_mfma_f32_16x16x32_bf16 v[4:7], v[200:203], v[192:195], v[4:7]
	v_mfma_f32_16x16x32_bf16 v[0:3], v[212:215], v[192:195], v[0:3]

	s_add_i32 s55, 0, 0x18000

	s_barrier
	ds_read_b128 v[128:131], v159 offset:32768
	ds_read_b128 v[132:135], v159 offset:33792
	ds_read_b128 v[136:139], v159 offset:34816
	ds_read_b128 v[150:153], v159 offset:35840
	s_add_u32 s20, s20, 0x160000
	s_addc_u32 s21, s21, 0
	s_mov_b32 m0, s28

	ds_read_b128 v[154:157], v160 offset:32768
	ds_read_b128 v[162:165], v160 offset:33792
	ds_read_b128 v[172:175], v160 offset:34816
	ds_read_b128 v[176:179], v160 offset:35840
	ds_read_b128 v[180:183], v160 offset:36864
	ds_read_b128 v[184:187], v160 offset:37888
	ds_read_b128 v[188:191], v160 offset:38912
	ds_read_b128 v[192:195], v160 offset:39936
	global_load_lds_dwordx4 v140, s[20:21]
	s_mov_b32 m0, s29
	s_nop 0

	global_load_lds_dwordx4 v142, s[20:21]
	s_waitcnt lgkmcnt(8)
	s_barrier
	s_waitcnt lgkmcnt(0)


	v_mfma_f32_16x16x32_bf16 v[124:127], v[128:131], v[154:157], v[124:127]
	v_mfma_f32_16x16x32_bf16 v[120:123], v[136:139], v[154:157], v[120:123]
	v_mfma_f32_16x16x32_bf16 v[116:119], v[128:131], v[172:175], v[116:119]
	v_mfma_f32_16x16x32_bf16 v[104:107], v[136:139], v[172:175], v[104:107]
	v_mfma_f32_16x16x32_bf16 v[96:99], v[128:131], v[180:183], v[96:99]
	v_mfma_f32_16x16x32_bf16 v[88:91], v[136:139], v[180:183], v[88:91]
	v_mfma_f32_16x16x32_bf16 v[80:83], v[128:131], v[188:191], v[80:83]
	v_mfma_f32_16x16x32_bf16 v[72:75], v[136:139], v[188:191], v[72:75]
	v_mfma_f32_16x16x32_bf16 v[124:127], v[132:135], v[162:165], v[124:127]
	v_mfma_f32_16x16x32_bf16 v[120:123], v[150:153], v[162:165], v[120:123]
	v_mfma_f32_16x16x32_bf16 v[116:119], v[132:135], v[176:179], v[116:119]
	v_mfma_f32_16x16x32_bf16 v[104:107], v[150:153], v[176:179], v[104:107]
	v_mfma_f32_16x16x32_bf16 v[96:99], v[132:135], v[184:187], v[96:99]
	v_mfma_f32_16x16x32_bf16 v[88:91], v[150:153], v[184:187], v[88:91]
	v_mfma_f32_16x16x32_bf16 v[80:83], v[132:135], v[192:195], v[80:83]
	v_mfma_f32_16x16x32_bf16 v[72:75], v[150:153], v[192:195], v[72:75]

	s_barrier
	s_add_i32 s20, 0, 0x1c000
	s_add_i32 s21, s55, s25


	s_mov_b32 m0, s21
	ds_read_b128 v[196:199], v161 offset:32768
	ds_read_b128 v[200:203], v161 offset:33792
	ds_read_b128 v[204:207], v161 offset:34816
	ds_read_b128 v[212:215], v161 offset:35840
	global_load_lds_dwordx4 v140, s[66:67]
	s_add_i32 m0, s21, 0x2000
	s_nop 0

	global_load_lds_dwordx4 v142, s[66:67]
	s_barrier
	s_waitcnt lgkmcnt(0)


	v_mfma_f32_16x16x32_bf16 v[112:115], v[196:199], v[154:157], v[112:115]
	v_mfma_f32_16x16x32_bf16 v[108:111], v[204:207], v[154:157], v[108:111]
	v_mfma_f32_16x16x32_bf16 v[100:103], v[196:199], v[172:175], v[100:103]
	v_mfma_f32_16x16x32_bf16 v[92:95], v[204:207], v[172:175], v[92:95]
	v_mfma_f32_16x16x32_bf16 v[84:87], v[196:199], v[180:183], v[84:87]
	v_mfma_f32_16x16x32_bf16 v[76:79], v[204:207], v[180:183], v[76:79]
	v_mfma_f32_16x16x32_bf16 v[68:71], v[196:199], v[188:191], v[68:71]
	v_mfma_f32_16x16x32_bf16 v[64:67], v[204:207], v[188:191], v[64:67]
	v_mfma_f32_16x16x32_bf16 v[112:115], v[200:203], v[162:165], v[112:115]
	v_mfma_f32_16x16x32_bf16 v[108:111], v[212:215], v[162:165], v[108:111]
	v_mfma_f32_16x16x32_bf16 v[100:103], v[200:203], v[176:179], v[100:103]
	v_mfma_f32_16x16x32_bf16 v[92:95], v[212:215], v[176:179], v[92:95]
	v_mfma_f32_16x16x32_bf16 v[84:87], v[200:203], v[184:187], v[84:87]
	v_mfma_f32_16x16x32_bf16 v[76:79], v[212:215], v[184:187], v[76:79]
	v_mfma_f32_16x16x32_bf16 v[68:71], v[200:203], v[192:195], v[68:71]
	v_mfma_f32_16x16x32_bf16 v[64:67], v[212:215], v[192:195], v[64:67]

	s_mov_b32 m0, s33

	s_barrier
	ds_read_b128 v[154:157], v160 offset:49152
	ds_read_b128 v[162:165], v160 offset:50176
	ds_read_b128 v[172:175], v160 offset:51200
	ds_read_b128 v[176:179], v160 offset:52224
	ds_read_b128 v[180:183], v160 offset:53248
	ds_read_b128 v[184:187], v160 offset:54272
	ds_read_b128 v[188:191], v160 offset:55296
	ds_read_b128 v[192:195], v160 offset:56320
	global_load_lds_dwordx4 v140, s[68:69]
	s_mov_b32 m0, s34
	s_nop 0

	global_load_lds_dwordx4 v142, s[68:69]
	s_barrier
	s_waitcnt lgkmcnt(0)


	v_mfma_f32_16x16x32_bf16 v[60:63], v[128:131], v[154:157], v[60:63]
	v_mfma_f32_16x16x32_bf16 v[56:59], v[136:139], v[154:157], v[56:59]
	v_mfma_f32_16x16x32_bf16 v[52:55], v[128:131], v[172:175], v[52:55]
	v_mfma_f32_16x16x32_bf16 v[40:43], v[136:139], v[172:175], v[40:43]
	v_mfma_f32_16x16x32_bf16 v[36:39], v[128:131], v[180:183], v[36:39]
	v_mfma_f32_16x16x32_bf16 v[24:27], v[136:139], v[180:183], v[24:27]
	v_mfma_f32_16x16x32_bf16 v[20:23], v[128:131], v[188:191], v[20:23]
	v_mfma_f32_16x16x32_bf16 v[8:11], v[136:139], v[188:191], v[8:11]
	v_mfma_f32_16x16x32_bf16 v[60:63], v[132:135], v[162:165], v[60:63]
	v_mfma_f32_16x16x32_bf16 v[56:59], v[150:153], v[162:165], v[56:59]
	v_mfma_f32_16x16x32_bf16 v[52:55], v[132:135], v[176:179], v[52:55]
	v_mfma_f32_16x16x32_bf16 v[40:43], v[150:153], v[176:179], v[40:43]
	v_mfma_f32_16x16x32_bf16 v[36:39], v[132:135], v[184:187], v[36:39]
	v_mfma_f32_16x16x32_bf16 v[24:27], v[150:153], v[184:187], v[24:27]
	v_mfma_f32_16x16x32_bf16 v[20:23], v[132:135], v[192:195], v[20:23]
	v_mfma_f32_16x16x32_bf16 v[8:11], v[150:153], v[192:195], v[8:11]

	s_barrier
	s_add_u32 s18, s18, 0x160080
	s_addc_u32 s19, s19, 0
	s_add_i32 s20, s20, s25
	s_mov_b32 m0, s20
	s_nop 0

	global_load_lds_dwordx4 v140, s[18:19]
	s_add_i32 m0, s20, 0x2000
	s_nop 0

	global_load_lds_dwordx4 v142, s[18:19]
	s_waitcnt vmcnt(6)
	s_barrier

	v_mfma_f32_16x16x32_bf16 v[48:51], v[196:199], v[154:157], v[48:51]
	v_mfma_f32_16x16x32_bf16 v[44:47], v[204:207], v[154:157], v[44:47]
	v_mfma_f32_16x16x32_bf16 v[32:35], v[196:199], v[172:175], v[32:35]
	v_mfma_f32_16x16x32_bf16 v[28:31], v[204:207], v[172:175], v[28:31]
	v_mfma_f32_16x16x32_bf16 v[16:19], v[196:199], v[180:183], v[16:19]
	v_mfma_f32_16x16x32_bf16 v[12:15], v[204:207], v[180:183], v[12:15]
	v_mfma_f32_16x16x32_bf16 v[4:7], v[196:199], v[188:191], v[4:7]
	v_mfma_f32_16x16x32_bf16 v[0:3], v[204:207], v[188:191], v[0:3]
	v_mfma_f32_16x16x32_bf16 v[48:51], v[200:203], v[162:165], v[48:51]
	v_mfma_f32_16x16x32_bf16 v[44:47], v[212:215], v[162:165], v[44:47]
	v_mfma_f32_16x16x32_bf16 v[32:35], v[200:203], v[176:179], v[32:35]
	v_mfma_f32_16x16x32_bf16 v[28:31], v[212:215], v[176:179], v[28:31]
	v_mfma_f32_16x16x32_bf16 v[16:19], v[200:203], v[184:187], v[16:19]
	v_mfma_f32_16x16x32_bf16 v[12:15], v[212:215], v[184:187], v[12:15]
	v_mfma_f32_16x16x32_bf16 v[4:7], v[200:203], v[192:195], v[4:7]
	v_mfma_f32_16x16x32_bf16 v[0:3], v[212:215], v[192:195], v[0:3]

	s_add_u32 s16, s16, 0x100
	s_addc_u32 s17, s17, 0
	s_add_u32 s52, s52, 0x100
	s_addc_u32 s53, s53, 0
	s_cmp_ge_i32 s54, s51
	s_mov_b32 s18, s54
	s_barrier
	s_cbranch_scc0 .LBB0_1258
	v_mov_b32_e32 v128, v210
	v_mov_b32_e32 v129, v169
	s_mov_b64 s[16:17], -1
	v_lshl_add_u32 v128, v128, 4, v129
	v_ashrrev_i32_e32 v150, 2, v128
	v_and_b32_e32 v129, 3, v129
	v_and_b32_e32 v128, -4, v128
	v_lshl_add_u32 v162, v129, 6, v128
	s_cmp_lt_i32 s2, 0
	v_lshlrev_b32_e32 v144, 4, v129
	s_cbranch_scc0 .LBB0_1261
	s_lshl_b32 s13, s50, 8
	s_add_i32 s13, s13, s30
	v_add_u32_e32 v128, s13, v150
	v_ashrrev_i32_e32 v129, 31, v128
	v_readlane_b32 s52, v254, 22
	v_lshlrev_b64 v[128:129], 13, v[128:129]
	v_readlane_b32 s66, v254, 36
	v_readlane_b32 s67, v254, 37
	s_lshl_b32 s16, s49, 8
	s_ashr_i32 s17, s16, 31
	v_lshl_add_u64 v[128:129], s[66:67], 0, v[128:129]
	v_lshl_add_u64 v[128:129], s[16:17], 2, v[128:129]
	s_lshl_b32 s16, s31, 2
	s_mov_b32 s17, s3
	v_lshl_add_u64 v[128:129], v[128:129], 0, s[16:17]
	v_lshl_add_u64 v[152:153], v[128:129], 0, v[144:145]
	global_load_dwordx4 v[164:167], v[152:153], off
	global_load_dwordx4 v[172:175], v[152:153], off offset:64
	global_load_dwordx4 v[176:179], v[152:153], off offset:512
	global_load_dwordx4 v[180:183], v[152:153], off offset:576
	v_add_co_u32_e32 v136, vcc, s37, v152
	ds_bpermute_b32 v138, v162, v124
	s_nop 0
	v_addc_co_u32_e32 v137, vcc, 0, v153, vcc
	global_load_dwordx4 v[184:187], v[136:137], off
	global_load_dwordx4 v[188:191], v[136:137], off offset:64
	global_load_dwordx4 v[192:195], v[136:137], off offset:512
	global_load_dwordx4 v[132:135], v[136:137], off offset:576
	v_add_co_u32_e32 v208, vcc, s38, v152
	ds_bpermute_b32 v139, v162, v125
	s_nop 0
	v_addc_co_u32_e32 v209, vcc, 0, v153, vcc
	global_load_dwordx4 v[196:199], v[208:209], off
	global_load_dwordx4 v[200:203], v[208:209], off offset:64
	global_load_dwordx4 v[204:207], v[208:209], off offset:512
	global_load_dwordx4 v[212:215], v[208:209], off offset:576
	v_add_co_u32_e32 v154, vcc, s39, v152
	ds_bpermute_b32 v156, v162, v126
	s_nop 0
	v_addc_co_u32_e32 v155, vcc, 0, v153, vcc
	global_load_dwordx4 v[216:219], v[154:155], off
	global_load_dwordx4 v[220:223], v[154:155], off offset:64
	global_load_dwordx4 v[224:227], v[154:155], off offset:512
	global_load_dwordx4 v[128:131], v[154:155], off offset:576
	ds_bpermute_b32 v157, v162, v127
	ds_bpermute_b32 v228, v162, v120
	ds_bpermute_b32 v229, v162, v121
	ds_bpermute_b32 v230, v162, v122
	ds_bpermute_b32 v231, v162, v123
	ds_bpermute_b32 v232, v162, v112
	ds_bpermute_b32 v233, v162, v113
	ds_bpermute_b32 v234, v162, v114
	ds_bpermute_b32 v235, v162, v115
	ds_bpermute_b32 v236, v162, v108
	ds_bpermute_b32 v237, v162, v109
	ds_bpermute_b32 v238, v162, v110
	ds_bpermute_b32 v239, v162, v111
	ds_bpermute_b32 v240, v162, v116
	ds_bpermute_b32 v241, v162, v117
	ds_bpermute_b32 v242, v162, v118
	ds_bpermute_b32 v243, v162, v119
	ds_bpermute_b32 v244, v162, v104
	ds_bpermute_b32 v245, v162, v105
	ds_bpermute_b32 v246, v162, v106
	ds_bpermute_b32 v247, v162, v107
	ds_bpermute_b32 v248, v162, v100
	ds_bpermute_b32 v249, v162, v101
	ds_bpermute_b32 v250, v162, v102
	ds_bpermute_b32 v251, v162, v103
	ds_bpermute_b32 v252, v162, v94
	ds_bpermute_b32 v253, v162, v95
	v_readlane_b32 s53, v254, 23
	v_readlane_b32 s54, v254, 24
	v_readlane_b32 s55, v254, 25
	v_readlane_b32 s56, v254, 26
	v_readlane_b32 s57, v254, 27
	v_readlane_b32 s58, v254, 28
	v_readlane_b32 s59, v254, 29
	v_readlane_b32 s60, v254, 30
	v_readlane_b32 s61, v254, 31
	v_readlane_b32 s62, v254, 32
	v_readlane_b32 s63, v254, 33
	v_readlane_b32 s64, v254, 34
	v_readlane_b32 s65, v254, 35
	s_mov_b64 s[16:17], 0
	s_waitcnt vmcnt(0) lgkmcnt(0)
	v_pk_add_f32 v[164:165], v[164:165], v[138:139]
	ds_bpermute_b32 v138, v162, v92
	ds_bpermute_b32 v139, v162, v93
	v_pk_add_f32 v[166:167], v[166:167], v[156:157]
	v_pk_add_f32 v[172:173], v[172:173], v[228:229]
	v_pk_add_f32 v[174:175], v[174:175], v[230:231]
	v_pk_add_f32 v[178:179], v[178:179], v[234:235]
	v_pk_add_f32 v[176:177], v[176:177], v[232:233]
	v_pk_add_f32 v[182:183], v[182:183], v[238:239]
	v_pk_add_f32 v[180:181], v[180:181], v[236:237]
	global_store_dwordx4 v[152:153], v[164:167], off
	global_store_dwordx4 v[152:153], v[172:175], off offset:64
	global_store_dwordx4 v[152:153], v[176:179], off offset:512
	global_store_dwordx4 v[152:153], v[180:183], off offset:576
	v_pk_add_f32 v[166:167], v[186:187], v[242:243]
	v_pk_add_f32 v[164:165], v[184:185], v[240:241]
	v_pk_add_f32 v[172:173], v[188:189], v[244:245]
	v_add_co_u32_e32 v156, vcc, s40, v152
	v_pk_add_f32 v[174:175], v[190:191], v[246:247]
	v_pk_add_f32 v[178:179], v[194:195], v[250:251]
	v_pk_add_f32 v[176:177], v[192:193], v[248:249]
	global_store_dwordx4 v[136:137], v[164:167], off
	global_store_dwordx4 v[136:137], v[172:175], off offset:64
	global_store_dwordx4 v[136:137], v[176:179], off offset:512
	v_addc_co_u32_e32 v157, vcc, 0, v153, vcc
	ds_bpermute_b32 v172, v162, v98
	ds_bpermute_b32 v173, v162, v99
	v_pk_add_f32 v[134:135], v[134:135], v[252:253]
	global_load_dwordx4 v[164:167], v[156:157], off
	s_waitcnt lgkmcnt(2)
	v_pk_add_f32 v[132:133], v[132:133], v[138:139]
	global_store_dwordx4 v[136:137], v[132:135], off offset:576
	ds_bpermute_b32 v132, v162, v96
	ds_bpermute_b32 v133, v162, v97
	ds_bpermute_b32 v136, v162, v90
	ds_bpermute_b32 v137, v162, v91
	ds_bpermute_b32 v138, v162, v88
	ds_bpermute_b32 v139, v162, v89
	s_waitcnt lgkmcnt(6)
	v_pk_add_f32 v[134:135], v[198:199], v[172:173]
	global_load_dwordx4 v[172:175], v[156:157], off offset:64
	s_waitcnt lgkmcnt(4)
	v_pk_add_f32 v[132:133], v[196:197], v[132:133]
	global_store_dwordx4 v[208:209], v[132:135], off
	ds_bpermute_b32 v180, v162, v76
	ds_bpermute_b32 v182, v162, v78
	s_waitcnt lgkmcnt(4)
	v_pk_add_f32 v[134:135], v[202:203], v[136:137]
	ds_bpermute_b32 v136, v162, v86
	ds_bpermute_b32 v137, v162, v87
	s_waitcnt lgkmcnt(4)
	v_pk_add_f32 v[132:133], v[200:201], v[138:139]
	ds_bpermute_b32 v138, v162, v84
	ds_bpermute_b32 v139, v162, v85
	global_store_dwordx4 v[208:209], v[132:135], off offset:64
	global_load_dwordx4 v[132:135], v[156:157], off offset:512
	s_waitcnt lgkmcnt(2)
	v_pk_add_f32 v[178:179], v[206:207], v[136:137]
	ds_bpermute_b32 v183, v162, v79
	s_waitcnt lgkmcnt(1)
	v_pk_add_f32 v[176:177], v[204:205], v[138:139]
	global_load_dwordx4 v[136:139], v[156:157], off offset:576
	ds_bpermute_b32 v181, v162, v77
	global_store_dwordx4 v[208:209], v[176:179], off offset:512
	v_add_co_u32_e32 v204, vcc, s41, v152
	s_waitcnt lgkmcnt(1)
	v_pk_add_f32 v[178:179], v[214:215], v[182:183]
	s_waitcnt lgkmcnt(0)
	v_pk_add_f32 v[176:177], v[212:213], v[180:181]
	ds_bpermute_b32 v180, v162, v80
	ds_bpermute_b32 v181, v162, v81
	ds_bpermute_b32 v182, v162, v82
	ds_bpermute_b32 v183, v162, v83
	v_addc_co_u32_e32 v205, vcc, 0, v153, vcc
	global_store_dwordx4 v[208:209], v[176:179], off offset:576
	global_load_dwordx4 v[176:179], v[204:205], off
	s_waitcnt lgkmcnt(0)
	v_pk_add_f32 v[182:183], v[218:219], v[182:183]
	global_load_dwordx4 v[184:187], v[204:205], off offset:64
	v_pk_add_f32 v[180:181], v[216:217], v[180:181]
	ds_bpermute_b32 v188, v162, v74
	ds_bpermute_b32 v189, v162, v75
	global_store_dwordx4 v[154:155], v[180:183], off
	ds_bpermute_b32 v180, v162, v72
	ds_bpermute_b32 v181, v162, v73
	ds_bpermute_b32 v192, v162, v68
	s_waitcnt lgkmcnt(3)
	v_pk_add_f32 v[182:183], v[222:223], v[188:189]
	global_load_dwordx4 v[188:191], v[204:205], off offset:512
	ds_bpermute_b32 v193, v162, v69
	s_waitcnt lgkmcnt(2)
	v_pk_add_f32 v[180:181], v[220:221], v[180:181]
	ds_bpermute_b32 v194, v162, v70
	ds_bpermute_b32 v195, v162, v71
	global_store_dwordx4 v[154:155], v[180:183], off offset:64
	global_load_dwordx4 v[180:183], v[204:205], off offset:576
	ds_bpermute_b32 v200, v162, v64
	ds_bpermute_b32 v196, v162, v66
	ds_bpermute_b32 v197, v162, v67
	ds_bpermute_b32 v201, v162, v65
	v_add_co_u32_e32 v206, vcc, s42, v152
	s_waitcnt lgkmcnt(4)
	v_pk_add_f32 v[194:195], v[226:227], v[194:195]
	v_pk_add_f32 v[192:193], v[224:225], v[192:193]
	v_addc_co_u32_e32 v207, vcc, 0, v153, vcc
	global_store_dwordx4 v[154:155], v[192:195], off offset:512
	global_load_dwordx4 v[192:195], v[206:207], off
	s_waitcnt lgkmcnt(1)
	v_pk_add_f32 v[130:131], v[130:131], v[196:197]
	s_waitcnt lgkmcnt(0)
	v_pk_add_f32 v[128:129], v[128:129], v[200:201]
	global_load_dwordx4 v[196:199], v[206:207], off offset:64
	ds_bpermute_b32 v202, v162, v62
	ds_bpermute_b32 v203, v162, v63
	global_store_dwordx4 v[154:155], v[128:131], off offset:576
	ds_bpermute_b32 v128, v162, v60
	ds_bpermute_b32 v129, v162, v61
	ds_bpermute_b32 v208, v162, v58
	ds_bpermute_b32 v209, v162, v59
	s_waitcnt vmcnt(18) lgkmcnt(4)
	v_pk_add_f32 v[130:131], v[166:167], v[202:203]
	ds_bpermute_b32 v154, v162, v56
	global_load_dwordx4 v[200:203], v[206:207], off offset:512
	ds_bpermute_b32 v155, v162, v57
	s_waitcnt lgkmcnt(4)
	v_pk_add_f32 v[128:129], v[164:165], v[128:129]
	global_load_dwordx4 v[164:167], v[206:207], off offset:576
	ds_bpermute_b32 v212, v162, v44
	global_store_dwordx4 v[156:157], v[128:131], off
	ds_bpermute_b32 v214, v162, v46
	ds_bpermute_b32 v215, v162, v47
	s_waitcnt vmcnt(19) lgkmcnt(5)
	v_pk_add_f32 v[130:131], v[174:175], v[208:209]
	v_add_co_u32_e32 v208, vcc, s43, v152
	s_waitcnt lgkmcnt(3)
	v_pk_add_f32 v[128:129], v[172:173], v[154:155]
	v_addc_co_u32_e32 v209, vcc, 0, v153, vcc
	global_store_dwordx4 v[156:157], v[128:131], off offset:64
	ds_bpermute_b32 v172, v162, v48
	ds_bpermute_b32 v173, v162, v49
	global_load_dwordx4 v[128:131], v[208:209], off
	global_load_dwordx4 v[152:155], v[208:209], off offset:64
	ds_bpermute_b32 v174, v162, v50
	ds_bpermute_b32 v175, v162, v51
	ds_bpermute_b32 v213, v162, v45
	s_waitcnt vmcnt(19) lgkmcnt(3)
	v_pk_add_f32 v[132:133], v[132:133], v[172:173]
	ds_bpermute_b32 v172, v162, v54
	ds_bpermute_b32 v173, v162, v55
	s_waitcnt lgkmcnt(3)
	v_pk_add_f32 v[134:135], v[134:135], v[174:175]
	global_store_dwordx4 v[156:157], v[132:135], off offset:512
	s_waitcnt vmcnt(16) lgkmcnt(0)
	v_pk_add_f32 v[174:175], v[178:179], v[172:173]
	v_pk_add_f32 v[134:135], v[138:139], v[214:215]
	v_pk_add_f32 v[132:133], v[136:137], v[212:213]
	global_store_dwordx4 v[156:157], v[132:135], off offset:576
	global_load_dwordx4 v[132:135], v[208:209], off offset:512
	ds_bpermute_b32 v156, v162, v52
	global_load_dwordx4 v[136:139], v[208:209], off offset:576
	ds_bpermute_b32 v157, v162, v53
	ds_bpermute_b32 v212, v162, v40
	ds_bpermute_b32 v214, v162, v42
	ds_bpermute_b32 v215, v162, v43
	ds_bpermute_b32 v213, v162, v41
	s_waitcnt lgkmcnt(4)
	v_pk_add_f32 v[172:173], v[176:177], v[156:157]
	global_store_dwordx4 v[204:205], v[172:175], off
	ds_bpermute_b32 v156, v162, v32
	ds_bpermute_b32 v157, v162, v33
	s_waitcnt vmcnt(19) lgkmcnt(3)
	v_pk_add_f32 v[174:175], v[186:187], v[214:215]
	s_waitcnt lgkmcnt(2)
	v_pk_add_f32 v[172:173], v[184:185], v[212:213]
	global_store_dwordx4 v[204:205], v[172:175], off offset:64
	ds_bpermute_b32 v172, v162, v34
	ds_bpermute_b32 v173, v162, v35
	ds_bpermute_b32 v176, v162, v28
	ds_bpermute_b32 v178, v162, v30
	ds_bpermute_b32 v179, v162, v31
	ds_bpermute_b32 v177, v162, v29
	s_waitcnt vmcnt(18) lgkmcnt(4)
	v_pk_add_f32 v[174:175], v[190:191], v[172:173]
	v_pk_add_f32 v[172:173], v[188:189], v[156:157]
	global_store_dwordx4 v[204:205], v[172:175], off offset:512
	ds_bpermute_b32 v156, v162, v36
	ds_bpermute_b32 v157, v162, v37
	s_waitcnt vmcnt(17) lgkmcnt(3)
	v_pk_add_f32 v[174:175], v[182:183], v[178:179]
	s_waitcnt lgkmcnt(2)
	v_pk_add_f32 v[172:173], v[180:181], v[176:177]
	global_store_dwordx4 v[204:205], v[172:175], off offset:576
	ds_bpermute_b32 v172, v162, v38
	ds_bpermute_b32 v173, v162, v39
	ds_bpermute_b32 v176, v162, v24
	ds_bpermute_b32 v178, v162, v26
	ds_bpermute_b32 v179, v162, v27
	ds_bpermute_b32 v177, v162, v25
	s_waitcnt vmcnt(16) lgkmcnt(4)
	v_pk_add_f32 v[174:175], v[194:195], v[172:173]
	v_pk_add_f32 v[172:173], v[192:193], v[156:157]
	global_store_dwordx4 v[206:207], v[172:175], off
	ds_bpermute_b32 v156, v162, v16
	ds_bpermute_b32 v157, v162, v17
	s_waitcnt vmcnt(16) lgkmcnt(3)
	v_pk_add_f32 v[174:175], v[198:199], v[178:179]
	s_waitcnt lgkmcnt(2)
	v_pk_add_f32 v[172:173], v[196:197], v[176:177]
	ds_bpermute_b32 v176, v162, v12
	ds_bpermute_b32 v178, v162, v14
	ds_bpermute_b32 v179, v162, v15
	ds_bpermute_b32 v177, v162, v13
	global_store_dwordx4 v[206:207], v[172:175], off offset:64
	ds_bpermute_b32 v172, v162, v18
	ds_bpermute_b32 v173, v162, v19
	s_waitcnt vmcnt(14) lgkmcnt(3)
	v_pk_add_f32 v[166:167], v[166:167], v[178:179]
	s_waitcnt lgkmcnt(2)
	v_pk_add_f32 v[164:165], v[164:165], v[176:177]
	global_store_dwordx4 v[206:207], v[164:167], off offset:576
	ds_bpermute_b32 v164, v162, v22
	s_waitcnt lgkmcnt(1)
	v_pk_add_f32 v[174:175], v[202:203], v[172:173]
	v_pk_add_f32 v[172:173], v[200:201], v[156:157]
	ds_bpermute_b32 v156, v162, v20
	ds_bpermute_b32 v157, v162, v21
	ds_bpermute_b32 v165, v162, v23
	global_store_dwordx4 v[206:207], v[172:175], off offset:512
	ds_bpermute_b32 v166, v162, v8
	ds_bpermute_b32 v172, v162, v10
	ds_bpermute_b32 v173, v162, v11
	ds_bpermute_b32 v167, v162, v9
	s_waitcnt vmcnt(13) lgkmcnt(4)
	v_pk_add_f32 v[130:131], v[130:131], v[164:165]
	v_pk_add_f32 v[128:129], v[128:129], v[156:157]
	global_store_dwordx4 v[208:209], v[128:131], off
	s_waitcnt vmcnt(13) lgkmcnt(1)
	s_nop 0
	v_pk_add_f32 v[130:131], v[154:155], v[172:173]
	s_waitcnt lgkmcnt(0)
	v_pk_add_f32 v[128:129], v[152:153], v[166:167]
	global_store_dwordx4 v[208:209], v[128:131], off offset:64
	ds_bpermute_b32 v128, v162, v4
	ds_bpermute_b32 v129, v162, v5
	ds_bpermute_b32 v130, v162, v6
	ds_bpermute_b32 v131, v162, v7
	ds_bpermute_b32 v152, v162, v0
	ds_bpermute_b32 v154, v162, v2
	ds_bpermute_b32 v155, v162, v3
	ds_bpermute_b32 v153, v162, v1
	s_waitcnt vmcnt(11) lgkmcnt(4)
	v_pk_add_f32 v[130:131], v[134:135], v[130:131]
	v_pk_add_f32 v[128:129], v[132:133], v[128:129]
	global_store_dwordx4 v[208:209], v[128:131], off offset:512
	s_waitcnt vmcnt(11) lgkmcnt(1)
	s_nop 0
	v_pk_add_f32 v[130:131], v[138:139], v[154:155]
	s_waitcnt lgkmcnt(0)
	v_pk_add_f32 v[128:129], v[136:137], v[152:153]
	global_store_dwordx4 v[208:209], v[128:131], off offset:576
